# XQ: mixer work queue split into 8 sub-queues by blockIdx&7 (per-XCD slice locality, 8 counters)
# baseline (speedup 1.0000x reference)
.Lfbp_out:
.LBB0_635:
	s_or_b64 exec, exec, s[0:1]
	v_mov_b32_e32 v255, -1
	v_readlane_b32 s0, v232, 14
	s_lshl_b32 s1, s2, 9
	s_nop 1
	s_and_b32 s0, s0, 28
	s_lshl_b32 s0, s0, 4
	s_add_u32 s0, s0, s1
	s_add_u32 s0, s0, 0x400
	s_add_u32 s44, s80, s0
	s_addc_u32 s45, s81, 0
	s_lshl_b64 s[0:1], s[2:3], 2
	s_add_u32 s48, s80, s0
	s_addc_u32 s49, s81, s1
	s_lshl_b32 s86, s2, 6
	s_lshl_b64 s[56:57], s[2:3], 20
	s_lshl_b32 s26, s2, 8
	s_lshl_b64 s[74:75], s[2:3], 15
	v_readlane_b32 s4, v232, 6
	s_add_u32 s4, s4, s0
	v_readlane_b32 s0, v232, 7
	s_addc_u32 s5, s0, s1
	v_writelane_b32 v232, s4, 39
	s_lshl_b64 s[0:1], s[86:87], 2
	s_waitcnt lgkmcnt(0)
	v_writelane_b32 v232, s5, 40
	v_readlane_b32 s4, v234, 20
	v_readlane_b32 s14, v234, 30
	v_readlane_b32 s15, v234, 31
	s_add_u32 s92, s14, s0
	s_barrier
	s_addc_u32 s93, s15, s1
	v_readlane_b32 s0, v232, 8
	v_readlane_b32 s19, v234, 35
	s_add_u32 s27, s0, s56
	v_readlane_b32 s0, v232, 9
	s_addc_u32 s50, s0, s57
	s_mov_b64 s[84:85], 0
	s_movk_i32 s19, 0x70
	v_readlane_b32 s5, v234, 21
	v_readlane_b32 s6, v234, 22
	v_readlane_b32 s7, v234, 23
	v_readlane_b32 s8, v234, 24
	v_readlane_b32 s9, v234, 25
	v_readlane_b32 s10, v234, 26
	v_readlane_b32 s11, v234, 27
	v_readlane_b32 s12, v234, 28
	v_readlane_b32 s13, v234, 29
	v_readlane_b32 s16, v234, 32
	v_readlane_b32 s17, v234, 33
	v_readlane_b32 s18, v234, 34
	s_branch .LBB0_640

.Lfp_atomic:
	global_atomic_add v0, v1, v160, s[44:45] sc0
	v_readlane_b32 s4, v232, 14
	s_nop 1
	s_lshr_b32 s4, s4, 2
	s_and_b32 s4, s4, 7
	s_add_u32 s4, s4, 0x200
	s_waitcnt vmcnt(0)
	v_lshlrev_b32_e32 v0, 3, v0
	v_add_u32_e32 v0, s4, v0
